# ping-pong attention loop: first PV V-fragment reads issued 5 MFMAs before the end of the QK stream (no LDS bubble between the two MFMA groups), lgkmcnt waits recomputed
# speedup vs baseline: 1.0189x; 1.0096x over previous
; template <int KB>
; __device__ __forceinline__ void qkt(f32x16& p0, f32x16& p1, const char* K_lds, int r32, int hi, const bf16x8* qr) {
;     p0 = f32x16{}; p1 = f32x16{};
;     const char* kb[4];
; #pragma unroll
;     for (int dd = 0; dd < 4; ++dd) kb[dd] = K_lds + KB * SHM_K + KSWZ(r32, (dd * 16 + hi * 8) * 2);
; #pragma unroll
;     for (int d0 = 0; d0 < 8; ++d0) { const char* a = kb[d0 & 3] + (d0 >> 2) * 128;
;         bf16x8 b0 = *reinterpret_cast<const bf16x8*>(a);
;         bf16x8 b1 = *reinterpret_cast<const bf16x8*>(a + 32 * 256);
;         p0 = __builtin_amdgcn_mfma_f32_32x32x16_bf16(b0, qr[d0], p0, 0, 0, 0);
;         p1 = __builtin_amdgcn_mfma_f32_32x32x16_bf16(b1, qr[d0], p1, 0, 0, 0); }
; }
; template <int VB>
; __device__ __forceinline__ void pv_tile(f32x16* o, int vb0, bf16x8 pa0, bf16x8 pa1, bf16x8 pa2, bf16x8 pa3) {
;     ...
;     PV_D0(0); PV_D0(1); PV_D0(2); PV_D0(3);
.Lp5_vw_a:
	global_load_dwordx2 v[146:147], v179, s[68:69] offset:-8
	s_add_u32 s98, s16, 0x40000
	s_addc_u32 s99, s17, 0
	global_load_dwordx4 v[130:133], v188, s[98:99]
	s_add_u32 s98, s16, 0x50000
	s_addc_u32 s99, s17, 0
	global_load_dwordx4 v[134:137], v188, s[98:99]
	s_add_u32 s98, s100, 0x40000
	s_addc_u32 s99, s101, 0
	global_load_dwordx4 v[138:141], v188, s[98:99]
	s_add_u32 s98, s100, 0x50000
	s_addc_u32 s99, s101, 0
	global_load_dwordx4 v[142:145], v188, s[98:99]
	ds_read_b128 v[66:69], v199 offset:49152
	ds_read_b128 v[82:85], v199 offset:57344
	ds_read_b128 v[172:175], v200 offset:49152
	ds_read_b128 v[232:235], v200 offset:57344
	ds_read_b128 v[236:239], v201 offset:49152
	ds_read_b128 v[240:243], v201 offset:57344
	ds_read_b128 v[244:247], v202 offset:49152
	s_waitcnt lgkmcnt(6)
	v_mfma_f32_32x32x16_bf16 v[66:81], v[66:69], v[126:129], 0
	s_waitcnt lgkmcnt(5)
	v_mfma_f32_32x32x16_bf16 v[82:97], v[82:85], v[126:129], 0
	s_waitcnt lgkmcnt(4)
	v_mfma_f32_32x32x16_bf16 v[66:81], v[172:175], v[122:125], v[66:81]
	ds_read_b128 v[172:175], v202 offset:57344
	s_waitcnt lgkmcnt(4)
	v_mfma_f32_32x32x16_bf16 v[82:97], v[232:235], v[122:125], v[82:97]
	ds_read_b128 v[232:235], v199 offset:49280
	s_waitcnt lgkmcnt(4)
	v_mfma_f32_32x32x16_bf16 v[66:81], v[236:239], v[118:121], v[66:81]
	ds_read_b128 v[236:239], v199 offset:57472
	s_waitcnt lgkmcnt(4)
	v_mfma_f32_32x32x16_bf16 v[82:97], v[240:243], v[118:121], v[82:97]
	ds_read_b128 v[240:243], v200 offset:49280
	s_waitcnt lgkmcnt(4)
	v_mfma_f32_32x32x16_bf16 v[66:81], v[244:247], v[114:117], v[66:81]
	ds_read_b128 v[244:247], v200 offset:57472
	s_waitcnt lgkmcnt(4)
	v_mfma_f32_32x32x16_bf16 v[82:97], v[172:175], v[114:117], v[82:97]
	ds_read_b128 v[172:175], v201 offset:49280
	s_waitcnt lgkmcnt(4)
	v_mfma_f32_32x32x16_bf16 v[66:81], v[232:235], v[110:113], v[66:81]
	ds_read_b128 v[232:235], v201 offset:57472
	s_waitcnt lgkmcnt(4)
	v_mfma_f32_32x32x16_bf16 v[82:97], v[236:239], v[110:113], v[82:97]
	ds_read_b128 v[236:239], v202 offset:49280
	s_waitcnt lgkmcnt(4)
	v_mfma_f32_32x32x16_bf16 v[66:81], v[240:243], v[106:109], v[66:81]
	ds_read_b64_tr_b16 v[212:213], v1 offset:0x0
	ds_read_b64_tr_b16 v[214:215], v1 offset:0x800
	ds_read_b64_tr_b16 v[216:217], v1 offset:0x200
	ds_read_b64_tr_b16 v[218:219], v1 offset:0xa00
	ds_read_b64_tr_b16 v[220:221], v1 offset:0x400
	ds_read_b64_tr_b16 v[222:223], v1 offset:0xc00
	ds_read_b64_tr_b16 v[224:225], v1 offset:0x600
	ds_read_b64_tr_b16 v[226:227], v1 offset:0xe00
	ds_read_b128 v[240:243], v202 offset:57472
	s_waitcnt lgkmcnt(12)
	v_mfma_f32_32x32x16_bf16 v[82:97], v[244:247], v[106:109], v[82:97]
	s_waitcnt lgkmcnt(11)
	v_mfma_f32_32x32x16_bf16 v[66:81], v[172:175], v[102:105], v[66:81]
	s_waitcnt lgkmcnt(10)
	v_mfma_f32_32x32x16_bf16 v[82:97], v[232:235], v[102:105], v[82:97]
	s_waitcnt lgkmcnt(9)
	v_mfma_f32_32x32x16_bf16 v[66:81], v[236:239], v[98:101], v[66:81]
	s_waitcnt lgkmcnt(0)
	v_mfma_f32_32x32x16_bf16 v[82:97], v[240:243], v[98:101], v[82:97]
	ds_read_b64_tr_b16 v[248:249], v1 offset:0x1000
	ds_read_b64_tr_b16 v[250:251], v1 offset:0x1800
	ds_read_b64_tr_b16 v[172:173], v1 offset:0x1200
	ds_read_b64_tr_b16 v[174:175], v1 offset:0x1a00
	ds_read_b64_tr_b16 v[232:233], v1 offset:0x1400
	ds_read_b64_tr_b16 v[234:235], v1 offset:0x1c00
	s_waitcnt lgkmcnt(13)
	v_mfma_f32_32x32x16_bf16 v[2:17], v[148:151], v[212:215], v[2:17]
	ds_read_b64_tr_b16 v[236:237], v1 offset:0x1600
	ds_read_b64_tr_b16 v[238:239], v1 offset:0x1e00
	s_waitcnt lgkmcnt(13)
	v_mfma_f32_32x32x16_bf16 v[50:65], v[148:151], v[216:219], v[50:65]
	ds_read_b64_tr_b16 v[240:241], v1 offset:0x2000
	ds_read_b64_tr_b16 v[242:243], v1 offset:0x2800
	s_waitcnt lgkmcnt(13)
	v_mfma_f32_32x32x16_bf16 v[34:49], v[148:151], v[220:223], v[34:49]
	ds_read_b64_tr_b16 v[244:245], v1 offset:0x2200
	ds_read_b64_tr_b16 v[246:247], v1 offset:0x2a00
	s_waitcnt lgkmcnt(13)
	v_mfma_f32_32x32x16_bf16 v[18:33], v[148:151], v[224:227], v[18:33]
	ds_read_b64_tr_b16 v[224:225], v1 offset:0x2400
	ds_read_b64_tr_b16 v[226:227], v1 offset:0x2c00
	s_waitcnt lgkmcnt(12)
	v_mfma_f32_32x32x16_bf16 v[2:17], v[152:155], v[248:251], v[2:17]
	ds_read_b64_tr_b16 v[248:249], v1 offset:0x2600
	ds_read_b64_tr_b16 v[250:251], v1 offset:0x2e00
	s_waitcnt lgkmcnt(12)
	v_mfma_f32_32x32x16_bf16 v[50:65], v[152:155], v[172:175], v[50:65]
	ds_read_b64_tr_b16 v[172:173], v1 offset:0x3000
	ds_read_b64_tr_b16 v[174:175], v1 offset:0x3800
	s_waitcnt lgkmcnt(12)
	v_mfma_f32_32x32x16_bf16 v[34:49], v[152:155], v[232:235], v[34:49]
	ds_read_b64_tr_b16 v[232:233], v1 offset:0x3200
	ds_read_b64_tr_b16 v[234:235], v1 offset:0x3a00
	s_waitcnt lgkmcnt(12)
	v_mfma_f32_32x32x16_bf16 v[18:33], v[152:155], v[236:239], v[18:33]
	ds_read_b64_tr_b16 v[236:237], v1 offset:0x3400
	ds_read_b64_tr_b16 v[238:239], v1 offset:0x3c00
	s_waitcnt lgkmcnt(12)
	v_mfma_f32_32x32x16_bf16 v[2:17], v[156:159], v[240:243], v[2:17]
	ds_read_b64_tr_b16 v[240:241], v1 offset:0x3600
	ds_read_b64_tr_b16 v[242:243], v1 offset:0x3e00
	s_waitcnt lgkmcnt(12)
	v_mfma_f32_32x32x16_bf16 v[50:65], v[156:159], v[244:247], v[50:65]
	s_waitcnt lgkmcnt(10)
	v_mfma_f32_32x32x16_bf16 v[34:49], v[156:159], v[224:227], v[34:49]
	s_waitcnt lgkmcnt(8)
	v_mfma_f32_32x32x16_bf16 v[18:33], v[156:159], v[248:251], v[18:33]
	s_waitcnt lgkmcnt(6)
	v_mfma_f32_32x32x16_bf16 v[2:17], v[208:211], v[172:175], v[2:17]
	s_waitcnt lgkmcnt(4)
	v_mfma_f32_32x32x16_bf16 v[50:65], v[208:211], v[232:235], v[50:65]
	s_waitcnt lgkmcnt(2)
	v_mfma_f32_32x32x16_bf16 v[34:49], v[208:211], v[236:239], v[34:49]
	s_waitcnt lgkmcnt(0)
	v_mfma_f32_32x32x16_bf16 v[18:33], v[208:211], v[240:243], v[18:33]
	s_waitcnt vmcnt(0)
	ds_write_b128 v204, v[138:141] offset:32768
	ds_write_b128 v204, v[142:145] offset:40960
	s_waitcnt lgkmcnt(0)
	s_barrier
; __device__ __forceinline__ void sel_mask_tile(f32x16& p0, f32x16& p1, unsigned wlo, unsigned whi, int hi) {
;     const unsigned NEGB = 0xff800000u;
;     const unsigned lo = wlo >> (4 * hi), h2 = whi >> (4 * hi);
; #pragma unroll
;     for (int r = 0; r < 16; ++r) {
;         const int c = (r & 3) + 8 * (r >> 2);
;         const unsigned m0 = (unsigned)__builtin_amdgcn_sbfe((int)lo, c, 1), m1 = (unsigned)__builtin_amdgcn_sbfe((int)h2, c, 1);
;         p0[r] = __uint_as_float((__float_as_uint(p0[r]) & m0) | (NEGB & ~m0));
;         p1[r] = __uint_as_float((__float_as_uint(p1[r]) & m1) | (NEGB & ~m1));
;     }
; }
; __device__ __forceinline__ void partialSM(f32x16& p0, f32x16& p1, float& m_reg, float& mn, float& alpha) {
;     float pmax = p0[0];
; #pragma unroll
;     for (int r = 1; r < 16; ++r) pmax = fmaxf(pmax, p0[r]);
; #pragma unroll
;     for (int r = 0; r < 16; ++r) pmax = fmaxf(pmax, p1[r]);
;     { auto rr = __builtin_amdgcn_permlane32_swap(__float_as_uint(pmax), __float_as_uint(pmax), false, false);
;       pmax = fmaxf(__uint_as_float(rr[0]), __uint_as_float(rr[1])); }
;     constexpr float C2 = 1.4426950408889634f * SCALE;
;     if (__builtin_expect(__all((pmax - m_reg) * SCALE <= THR), 1)) { mn = m_reg; alpha = 1.f; }
;     else { mn = fmaxf(m_reg, pmax); alpha = __builtin_amdgcn_exp2f((m_reg - mn) * C2); m_reg = mn; }
	s_nop 0
	s_waitcnt vmcnt(4)
	v_lshrrev_b32_e32 v160, v163, v146
	v_lshrrev_b32_e32 v161, v163, v147
	v_bfe_i32 v146, v160, 0, 1
	v_bfe_i32 v147, v161, 0, 1
	v_bitop3_b32 v146, v66, s74, v146 bitop3:0xe4
	v_bitop3_b32 v66, v82, s74, v147 bitop3:0xe4
	v_bfe_i32 v82, v160, 1, 1
	v_bfe_i32 v147, v161, 1, 1
	v_bitop3_b32 v82, v67, s74, v82 bitop3:0xe4
	v_bitop3_b32 v67, v83, s74, v147 bitop3:0xe4
	v_bfe_i32 v83, v160, 2, 1
	v_bfe_i32 v147, v161, 2, 1
	v_bitop3_b32 v83, v68, s74, v83 bitop3:0xe4
	v_bitop3_b32 v68, v84, s74, v147 bitop3:0xe4
	v_bfe_i32 v84, v160, 3, 1
	v_bfe_i32 v148, v161, 3, 1
	v_bitop3_b32 v147, v69, s74, v84 bitop3:0xe4
	v_bfe_i32 v84, v160, 8, 1
	v_bitop3_b32 v69, v85, s74, v148 bitop3:0xe4
	v_bfe_i32 v85, v161, 8, 1
	v_bitop3_b32 v148, v70, s74, v84 bitop3:0xe4
	v_bfe_i32 v84, v160, 9, 1
	v_bitop3_b32 v70, v86, s74, v85 bitop3:0xe4
	v_bfe_i32 v85, v161, 9, 1
	v_bitop3_b32 v149, v71, s74, v84 bitop3:0xe4
	v_bfe_i32 v84, v160, 10, 1
	v_bitop3_b32 v71, v87, s74, v85 bitop3:0xe4
	v_bfe_i32 v85, v161, 10, 1
	v_bitop3_b32 v87, v72, s74, v84 bitop3:0xe4
	v_bfe_i32 v84, v160, 11, 1
	v_bitop3_b32 v72, v88, s74, v85 bitop3:0xe4
	v_bfe_i32 v85, v161, 11, 1
	v_bitop3_b32 v88, v73, s74, v84 bitop3:0xe4
	v_bfe_i32 v73, v160, 16, 1
	v_bitop3_b32 v84, v89, s74, v85 bitop3:0xe4
	v_bfe_i32 v85, v161, 16, 1
	v_bitop3_b32 v89, v74, s74, v73 bitop3:0xe4
	v_bfe_i32 v73, v160, 17, 1
	v_bfe_i32 v74, v161, 17, 1
	v_bitop3_b32 v85, v90, s74, v85 bitop3:0xe4
	v_bitop3_b32 v90, v75, s74, v73 bitop3:0xe4
	v_bitop3_b32 v86, v91, s74, v74 bitop3:0xe4
	v_bfe_i32 v73, v160, 18, 1
	v_bfe_i32 v74, v161, 18, 1
	v_bitop3_b32 v91, v76, s74, v73 bitop3:0xe4
	v_bitop3_b32 v76, v92, s74, v74 bitop3:0xe4
	v_bfe_i32 v73, v160, 19, 1
	v_bfe_i32 v74, v161, 19, 1
	v_bitop3_b32 v92, v77, s74, v73 bitop3:0xe4
	v_bitop3_b32 v77, v93, s74, v74 bitop3:0xe4
	v_bfe_i32 v73, v160, 24, 1
	v_bfe_i32 v74, v161, 24, 1
	v_bitop3_b32 v93, v78, s74, v73 bitop3:0xe4
	v_bitop3_b32 v78, v94, s74, v74 bitop3:0xe4
	v_bfe_i32 v73, v160, 25, 1
	v_bfe_i32 v74, v161, 25, 1
	v_bitop3_b32 v79, v79, s74, v73 bitop3:0xe4
	v_bitop3_b32 v73, v95, s74, v74 bitop3:0xe4
	v_bfe_i32 v74, v160, 26, 1
	v_bfe_i32 v75, v161, 26, 1
	v_bitop3_b32 v80, v80, s74, v74 bitop3:0xe4
	v_bitop3_b32 v74, v96, s74, v75 bitop3:0xe4
	v_bfe_i32 v75, v160, 27, 1
	v_bfe_i32 v94, v161, 27, 1
	v_bitop3_b32 v81, v81, s74, v75 bitop3:0xe4
	v_bitop3_b32 v75, v97, s74, v94 bitop3:0xe4
	v_max_f32_e32 v94, v146, v82
	v_max3_f32 v94, v94, v83, v147
	v_max3_f32 v94, v94, v148, v149
	v_max3_f32 v94, v94, v87, v88
	v_max3_f32 v94, v94, v89, v90
	v_max3_f32 v94, v94, v91, v92
	v_max3_f32 v94, v94, v93, v79
	v_max3_f32 v94, v94, v80, v81
	v_max3_f32 v94, v94, v66, v67
	v_max3_f32 v94, v94, v68, v69
	v_max3_f32 v94, v94, v70, v71
	v_max3_f32 v94, v94, v72, v84
	v_max3_f32 v94, v94, v85, v86
	v_max3_f32 v94, v94, v76, v77
	v_max3_f32 v94, v94, v78, v73
	v_max3_f32 v94, v94, v74, v75
	v_mov_b32_e32 v95, v94
	s_nop 1
	v_permlane32_swap_b32_e32 v94, v95
	v_max_f32_e32 v94, v94, v95
	v_sub_f32_e32 v95, v94, v206
	v_mul_f32_e32 v95, 0x3db504f3, v95
	v_cmp_ge_f32_e32 vcc, s75, v95
	s_cmp_eq_u64 vcc, exec
	s_cselect_b64 s[6:7], -1, 0
	s_cbranch_scc1 .Lp5_b1fast
	v_max_f32_e32 v94, v206, v94
	v_sub_f32_e32 v96, v206, v94
	v_mul_f32_e32 v96, 0x3e0293ee, v96
	v_exp_f32_e32 v96, v96

; template <int KB>
; __device__ __forceinline__ void qkt(f32x16& p0, f32x16& p1, const char* K_lds, int r32, int hi, const bf16x8* qr) {
;     p0 = f32x16{}; p1 = f32x16{};
;     const char* kb[4];
; #pragma unroll
;     for (int dd = 0; dd < 4; ++dd) kb[dd] = K_lds + KB * SHM_K + KSWZ(r32, (dd * 16 + hi * 8) * 2);
; #pragma unroll
;     for (int d0 = 0; d0 < 8; ++d0) { const char* a = kb[d0 & 3] + (d0 >> 2) * 128;
;         bf16x8 b0 = *reinterpret_cast<const bf16x8*>(a);
;         bf16x8 b1 = *reinterpret_cast<const bf16x8*>(a + 32 * 256);
;         p0 = __builtin_amdgcn_mfma_f32_32x32x16_bf16(b0, qr[d0], p0, 0, 0, 0);
;         p1 = __builtin_amdgcn_mfma_f32_32x32x16_bf16(b1, qr[d0], p1, 0, 0, 0); }
; }
; template <int VB>
; __device__ __forceinline__ void pv_tile(f32x16* o, int vb0, bf16x8 pa0, bf16x8 pa1, bf16x8 pa2, bf16x8 pa3) {
;     ...
;     PV_D0(0); PV_D0(1); PV_D0(2); PV_D0(3);
.Lp5_a2:
	ds_read_b128 v[66:69], v199 offset:32768
	ds_read_b128 v[70:73], v199 offset:40960
	ds_read_b128 v[172:175], v200 offset:32768
	ds_read_b128 v[224:227], v200 offset:40960
	ds_read_b128 v[232:235], v201 offset:32768
	ds_read_b128 v[236:239], v201 offset:40960
	ds_read_b128 v[240:243], v202 offset:32768
	ds_read_b128 v[244:247], v202 offset:40960
	s_waitcnt lgkmcnt(7)
	v_mfma_f32_32x32x16_bf16 v[82:97], v[66:69], v[126:129], 0
	s_waitcnt lgkmcnt(6)
	v_mfma_f32_32x32x16_bf16 v[66:81], v[70:73], v[126:129], 0
	s_waitcnt lgkmcnt(5)
	v_mfma_f32_32x32x16_bf16 v[82:97], v[172:175], v[122:125], v[82:97]
	ds_read_b128 v[172:175], v199 offset:32896
	s_waitcnt lgkmcnt(5)
	v_mfma_f32_32x32x16_bf16 v[66:81], v[224:227], v[122:125], v[66:81]
	ds_read_b128 v[224:227], v199 offset:41088
	s_waitcnt lgkmcnt(5)
	v_mfma_f32_32x32x16_bf16 v[82:97], v[232:235], v[118:121], v[82:97]
	ds_read_b128 v[232:235], v200 offset:32896
	s_waitcnt lgkmcnt(5)
	v_mfma_f32_32x32x16_bf16 v[66:81], v[236:239], v[118:121], v[66:81]
	ds_read_b128 v[236:239], v200 offset:41088
	s_waitcnt lgkmcnt(5)
	v_mfma_f32_32x32x16_bf16 v[82:97], v[240:243], v[114:117], v[82:97]
	ds_read_b128 v[240:243], v201 offset:32896
	s_waitcnt lgkmcnt(5)
	v_mfma_f32_32x32x16_bf16 v[66:81], v[244:247], v[114:117], v[66:81]
	ds_read_b128 v[244:247], v201 offset:41088
	s_waitcnt lgkmcnt(5)
	v_mfma_f32_32x32x16_bf16 v[82:97], v[172:175], v[110:113], v[82:97]
	ds_read_b128 v[172:175], v202 offset:32896
	s_waitcnt lgkmcnt(5)
	v_mfma_f32_32x32x16_bf16 v[66:81], v[224:227], v[110:113], v[66:81]
	ds_read_b128 v[224:227], v202 offset:41088
	s_waitcnt lgkmcnt(5)
	v_mfma_f32_32x32x16_bf16 v[82:97], v[232:235], v[106:109], v[82:97]
	ds_read_b64_tr_b16 v[212:213], v1 offset:0x4000
	ds_read_b64_tr_b16 v[214:215], v1 offset:0x4800
	ds_read_b64_tr_b16 v[216:217], v1 offset:0x4200
	ds_read_b64_tr_b16 v[218:219], v1 offset:0x4a00
	ds_read_b64_tr_b16 v[220:221], v1 offset:0x4400
	ds_read_b64_tr_b16 v[222:223], v1 offset:0x4c00
	ds_read_b64_tr_b16 v[248:249], v1 offset:0x4600
	ds_read_b64_tr_b16 v[250:251], v1 offset:0x4e00
	s_waitcnt lgkmcnt(12)
	v_mfma_f32_32x32x16_bf16 v[66:81], v[236:239], v[106:109], v[66:81]
	s_waitcnt lgkmcnt(11)
	v_mfma_f32_32x32x16_bf16 v[82:97], v[240:243], v[102:105], v[82:97]
	s_waitcnt lgkmcnt(10)
	v_mfma_f32_32x32x16_bf16 v[66:81], v[244:247], v[102:105], v[66:81]
	s_waitcnt lgkmcnt(9)
	v_mfma_f32_32x32x16_bf16 v[82:97], v[172:175], v[98:101], v[82:97]
	s_waitcnt lgkmcnt(8)
	v_mfma_f32_32x32x16_bf16 v[66:81], v[224:227], v[98:101], v[66:81]
	s_add_i32 s82, s82, 2
	s_cmp_le_u32 s82, s81
	s_cselect_b64 s[36:37], -1, 0
	s_cselect_b32 s76, 1, 0
	s_cmp_gt_u32 s82, s81
	s_cbranch_scc1 .Lp5_skip_ld
.LBB0_1305:
	ds_read_b64_tr_b16 v[172:173], v1 offset:0x5000
	ds_read_b64_tr_b16 v[174:175], v1 offset:0x5800
	ds_read_b64_tr_b16 v[224:225], v1 offset:0x5200
	ds_read_b64_tr_b16 v[226:227], v1 offset:0x5a00
	ds_read_b64_tr_b16 v[232:233], v1 offset:0x5400
	ds_read_b64_tr_b16 v[234:235], v1 offset:0x5c00
	s_waitcnt lgkmcnt(12)
	v_mfma_f32_32x32x16_bf16 v[2:17], v[146:149], v[212:215], v[2:17]
	ds_read_b64_tr_b16 v[236:237], v1 offset:0x5600
	ds_read_b64_tr_b16 v[238:239], v1 offset:0x5e00
	s_waitcnt lgkmcnt(12)
	v_mfma_f32_32x32x16_bf16 v[50:65], v[146:149], v[216:219], v[50:65]
	ds_read_b64_tr_b16 v[240:241], v1 offset:0x6000
	ds_read_b64_tr_b16 v[242:243], v1 offset:0x6800
	s_waitcnt lgkmcnt(12)
	v_mfma_f32_32x32x16_bf16 v[34:49], v[146:149], v[220:223], v[34:49]
	ds_read_b64_tr_b16 v[244:245], v1 offset:0x6200
	ds_read_b64_tr_b16 v[246:247], v1 offset:0x6a00
	s_waitcnt lgkmcnt(12)
	v_mfma_f32_32x32x16_bf16 v[18:33], v[146:149], v[248:251], v[18:33]
	ds_read_b64_tr_b16 v[248:249], v1 offset:0x6400
	ds_read_b64_tr_b16 v[250:251], v1 offset:0x6c00
	s_waitcnt lgkmcnt(12)
	v_mfma_f32_32x32x16_bf16 v[2:17], v[150:153], v[172:175], v[2:17]
	ds_read_b64_tr_b16 v[172:173], v1 offset:0x6600
	ds_read_b64_tr_b16 v[174:175], v1 offset:0x6e00
	s_waitcnt lgkmcnt(12)
	v_mfma_f32_32x32x16_bf16 v[50:65], v[150:153], v[224:227], v[50:65]
	ds_read_b64_tr_b16 v[224:225], v1 offset:0x7000
	ds_read_b64_tr_b16 v[226:227], v1 offset:0x7800
	s_waitcnt lgkmcnt(12)
	v_mfma_f32_32x32x16_bf16 v[34:49], v[150:153], v[232:235], v[34:49]
	ds_read_b64_tr_b16 v[232:233], v1 offset:0x7200
	ds_read_b64_tr_b16 v[234:235], v1 offset:0x7a00
	s_waitcnt lgkmcnt(12)
	v_mfma_f32_32x32x16_bf16 v[18:33], v[150:153], v[236:239], v[18:33]
	ds_read_b64_tr_b16 v[236:237], v1 offset:0x7400
	ds_read_b64_tr_b16 v[238:239], v1 offset:0x7c00
	s_waitcnt lgkmcnt(12)
	v_mfma_f32_32x32x16_bf16 v[2:17], v[154:157], v[240:243], v[2:17]
	ds_read_b64_tr_b16 v[240:241], v1 offset:0x7600
	ds_read_b64_tr_b16 v[242:243], v1 offset:0x7e00
	s_waitcnt lgkmcnt(12)
	v_mfma_f32_32x32x16_bf16 v[50:65], v[154:157], v[244:247], v[50:65]
	s_waitcnt lgkmcnt(10)
	v_mfma_f32_32x32x16_bf16 v[34:49], v[154:157], v[248:251], v[34:49]
	s_waitcnt lgkmcnt(8)
	v_mfma_f32_32x32x16_bf16 v[18:33], v[154:157], v[172:175], v[18:33]
	s_waitcnt lgkmcnt(6)
	v_mfma_f32_32x32x16_bf16 v[2:17], v[158:161], v[224:227], v[2:17]
	s_waitcnt lgkmcnt(4)
	v_mfma_f32_32x32x16_bf16 v[50:65], v[158:161], v[232:235], v[50:65]
	s_waitcnt lgkmcnt(2)
	v_mfma_f32_32x32x16_bf16 v[34:49], v[158:161], v[236:239], v[34:49]
	s_waitcnt lgkmcnt(0)
	v_mfma_f32_32x32x16_bf16 v[18:33], v[158:161], v[240:243], v[18:33]
	s_cmp_eq_u64 s[36:37], 0
	s_cbranch_scc1 .Lp5_kw2_skip
	s_waitcnt vmcnt(0)
	ds_write_b128 v204, v[138:141] offset:49152
	ds_write_b128 v204, v[142:145] offset:57344
